# v44 + y stores sc1 nt instead of nt
# speedup vs baseline: 1.0010x; 1.0010x over previous
; __device__ __forceinline__ float rstd_of(float ss) { return __builtin_amdgcn_rsqf(ss * (1.0f / DM) + EPS); }
; __device__ __forceinline__ float atomic_read_f32(float* p) { return __hip_atomic_fetch_add(p, 0.0f, __ATOMIC_RELAXED, __HIP_MEMORY_SCOPE_AGENT); }
; __device__ __forceinline__ void down_sample_tile(Frame& F, int tile, float* SS2, unsigned* cntb, float* YO) {
;     ...
;     float s = 0.f; if ((F.tid & 7) == 0) s = atomic_read_f32(SS2 + row);
;     const float rs = rstd_of(__shfl(s, F.lane & ~7));
;     *(f32x4v*)(YO + off) = (f32x4v){x0[0] * rs * ga[0], x0[1] * rs * ga[1], x0[2] * rs * ga[2], x0[3] * rs * ga[3]};
;     *(f32x4v*)(YO + off + 4) = (f32x4v){x1[0] * rs * gb[0], x1[1] * rs * gb[1], x1[2] * rs * gb[2], x1[3] * rs * gb[3]};
.LBB0_1044:
	s_or_b64 exec, exec, s[8:9]
	v_and_or_b32 v20, v0, 56, v22
	v_lshlrev_b32_e32 v20, 2, v20
	s_waitcnt vmcnt(0)
	ds_bpermute_b32 v20, v20, v23
	v_mov_b32_e32 v21, 0x358637bd
	v_lshl_add_u64 v[10:11], v[10:11], 2, s[48:49]
	v_mov_b32_e32 v139, v70
	v_mov_b32_e32 v155, v1
	s_waitcnt lgkmcnt(0)
	v_fmac_f32_e32 v21, 0x3a800000, v20
	v_rsq_f32_e32 v20, v21
	s_nop 0
	v_pk_mul_f32 v[12:13], v[12:13], v[20:21] op_sel_hi:[1,0]
	v_pk_mul_f32 v[16:17], v[16:17], v[20:21] op_sel_hi:[1,0]
	v_pk_mul_f32 v[14:15], v[14:15], v[20:21] op_sel_hi:[1,0]
	v_pk_mul_f32 v[18:19], v[18:19], v[20:21] op_sel_hi:[1,0]
	v_pk_mul_f32 v[8:9], v[8:9], v[16:17]
	v_pk_mul_f32 v[6:7], v[6:7], v[12:13]
	v_pk_mul_f32 v[4:5], v[4:5], v[18:19]
	v_pk_mul_f32 v[2:3], v[2:3], v[14:15]
	global_store_dwordx4 v[10:11], v[6:9], off sc1 nt
	global_store_dwordx4 v[10:11], v[2:5], off offset:16 sc1 nt
	s_barrier

; __device__ __forceinline__ float rstd_of(float ss) { return __builtin_amdgcn_rsqf(ss * (1.0f / DM) + EPS); }
; __device__ __forceinline__ float atomic_read_f32(float* p) { return __hip_atomic_fetch_add(p, 0.0f, __ATOMIC_RELAXED, __HIP_MEMORY_SCOPE_AGENT); }
;     __device__ __forceinline__ void operator()(pg8::f32x4 (&acc)[2][2][4][2], const Unit& u, int wr, int wc, int fr, int fq) const {
;     ...
;         pg8::f32x4 gn[2];
; #pragma unroll
;         for (int bj = 0; bj < 2; ++bj) gn[bj] = *(const pg8::f32x4*)(gain + cbase + bj * HALF);
; #pragma unroll
;         for (int ai = 0; ai < 2; ++ai)
; #pragma unroll
;             for (int m = 0; m < 4; ++m)
; #pragma unroll
;                 for (int p = 0; p < 2; ++p) { const int row = row0 + ai * HALF + m * 16 + 8 * p + rr; float s = 0.f; if (sl == 0) s = atomic_read_f32(SS2 + row); const float rs = rstd_of(__shfl(s, lane & ~7));
; #pragma unroll
;                     for (int bj = 0; bj < 2; ++bj) *(pg8::f32x4*)(YO + (size_t)row * DM + cbase + bj * HALF) = acc[ai][bj][m][p] * rs * gn[bj]; }
.LBB0_1101:
	v_readlane_b32 s64, v238, 29
	v_readlane_b32 s78, v238, 43
	v_readlane_b32 s79, v238, 44
	v_mov_b32_e32 v176, 0
	v_mov_b32_e32 v177, 0
	v_lshl_add_u64 v[2:3], v[150:151], 2, s[78:79]
	global_load_dwordx4 v[6:9], v[2:3], off
	s_waitcnt lgkmcnt(0)
	global_load_dwordx4 v[2:5], v[2:3], off offset:512
	v_readlane_b32 s65, v238, 30
	v_readlane_b32 s66, v238, 31
	v_readlane_b32 s67, v238, 32
	v_readlane_b32 s68, v238, 33
	v_readlane_b32 s69, v238, 34
	v_readlane_b32 s70, v238, 35
	v_readlane_b32 s71, v238, 36
	v_readlane_b32 s72, v238, 37
	v_readlane_b32 s73, v238, 38
	v_readlane_b32 s74, v238, 39
	v_readlane_b32 s75, v238, 40
	v_readlane_b32 s76, v238, 41
	v_readlane_b32 s77, v238, 42
	v_lshl_add_u64 v[228:229], v[152:153], 2, s[14:15]
	global_load_dword v194, v[228:229], off sc1
	global_load_dword v195, v[228:229], off offset:32 sc1
	global_load_dword v196, v[228:229], off offset:64 sc1
	global_load_dword v197, v[228:229], off offset:96 sc1
	global_load_dword v198, v[228:229], off offset:128 sc1
	global_load_dword v199, v[228:229], off offset:160 sc1
	global_load_dword v200, v[228:229], off offset:192 sc1
	global_load_dword v201, v[228:229], off offset:224 sc1
	global_load_dword v202, v[228:229], off offset:512 sc1
	global_load_dword v203, v[228:229], off offset:544 sc1
	global_load_dword v204, v[228:229], off offset:576 sc1
	global_load_dword v205, v[228:229], off offset:608 sc1
	global_load_dword v206, v[228:229], off offset:640 sc1
	global_load_dword v207, v[228:229], off offset:672 sc1
	global_load_dword v208, v[228:229], off offset:704 sc1
	global_load_dword v209, v[228:229], off offset:736 sc1
	s_waitcnt vmcnt(15)
	v_mov_b32_e32 v177, v194
	v_lshlrev_b64 v[180:181], 12, v[152:153]
	v_lshl_add_u64 v[180:181], s[48:49], 0, v[180:181]
	v_lshl_add_u64 v[180:181], v[150:151], 2, v[180:181]
	s_waitcnt lgkmcnt(0)
	v_fmamk_f32 v177, v177, 0x3a800000, v172
	v_rsq_f32_e32 v178, v177
	s_nop 0
	v_pk_mul_f32 v[128:129], v[128:129], v[178:179] op_sel_hi:[1,0]
	v_pk_mul_f32 v[124:125], v[124:125], v[178:179] op_sel_hi:[1,0]
	v_pk_mul_f32 v[126:127], v[126:127], v[178:179] op_sel_hi:[1,0]
	v_pk_mul_f32 v[178:179], v[122:123], v[178:179] op_sel_hi:[1,0]
	v_pk_mul_f32 v[124:125], v[8:9], v[124:125]
	v_pk_mul_f32 v[122:123], v[6:7], v[128:129]
	global_store_dwordx4 v[180:181], v[122:125], off sc1 nt
	s_nop 1
	v_pk_mul_f32 v[124:125], v[4:5], v[178:179]
	v_pk_mul_f32 v[122:123], v[2:3], v[126:127]
	global_store_dwordx4 v[180:181], v[122:125], off offset:512 sc1 nt
	s_nop 0
	s_waitcnt vmcnt(16)
	v_mov_b32_e32 v122, v195
	v_lshlrev_b64 v[124:125], 12, v[156:157]
	v_lshl_add_u64 v[124:125], s[48:49], 0, v[124:125]
	v_lshl_add_u64 v[124:125], v[150:151], 2, v[124:125]
	s_waitcnt lgkmcnt(0)
	v_fmamk_f32 v122, v122, 0x3a800000, v172
	v_rsq_f32_e32 v122, v122
	s_nop 0
	v_pk_mul_f32 v[116:117], v[116:117], v[122:123] op_sel_hi:[1,0]
	v_pk_mul_f32 v[118:119], v[118:119], v[122:123] op_sel_hi:[1,0]
	v_pk_mul_f32 v[126:127], v[114:115], v[122:123] op_sel_hi:[1,0]
	v_pk_mul_f32 v[120:121], v[120:121], v[122:123] op_sel_hi:[1,0]
	v_pk_mul_f32 v[116:117], v[8:9], v[116:117]
	v_pk_mul_f32 v[114:115], v[6:7], v[118:119]
	global_store_dwordx4 v[124:125], v[114:117], off sc1 nt
	s_nop 1
	v_pk_mul_f32 v[116:117], v[4:5], v[126:127]
	v_pk_mul_f32 v[114:115], v[2:3], v[120:121]
	global_store_dwordx4 v[124:125], v[114:117], off offset:512 sc1 nt
	s_nop 1
	v_or_b32_e32 v114, 16, v152
	v_ashrrev_i32_e32 v115, 31, v114
	v_mov_b32_e32 v116, 0
	v_mov_b32_e32 v117, 0
	s_nop 0
	s_waitcnt vmcnt(17)
	v_mov_b32_e32 v117, v196
	v_lshlrev_b64 v[114:115], 12, v[114:115]
	v_lshl_add_u64 v[114:115], s[48:49], 0, v[114:115]
	v_lshl_add_u64 v[114:115], v[150:151], 2, v[114:115]
	s_waitcnt lgkmcnt(0)
	v_fmamk_f32 v117, v117, 0x3a800000, v172
	v_rsq_f32_e32 v118, v117
	s_nop 0
	v_pk_mul_f32 v[106:107], v[106:107], v[118:119] op_sel_hi:[1,0]
	v_pk_mul_f32 v[120:121], v[108:109], v[118:119] op_sel_hi:[1,0]
	v_pk_mul_f32 v[110:111], v[110:111], v[118:119] op_sel_hi:[1,0]
	v_pk_mul_f32 v[112:113], v[112:113], v[118:119] op_sel_hi:[1,0]
	v_pk_mul_f32 v[108:109], v[8:9], v[106:107]
	v_pk_mul_f32 v[106:107], v[6:7], v[120:121]
	global_store_dwordx4 v[114:115], v[106:109], off sc1 nt
	s_nop 1
	v_pk_mul_f32 v[108:109], v[4:5], v[110:111]
	v_pk_mul_f32 v[106:107], v[2:3], v[112:113]
	global_store_dwordx4 v[114:115], v[106:109], off offset:512 sc1 nt
	s_nop 1
	v_or_b32_e32 v106, 24, v152
	v_ashrrev_i32_e32 v107, 31, v106
	s_nop 0
	s_waitcnt vmcnt(18)
	v_mov_b32_e32 v108, v197
	v_lshlrev_b64 v[106:107], 12, v[106:107]
	v_lshl_add_u64 v[106:107], s[48:49], 0, v[106:107]
	v_lshl_add_u64 v[106:107], v[150:151], 2, v[106:107]
	s_waitcnt lgkmcnt(0)
	v_fmamk_f32 v108, v108, 0x3a800000, v172
	v_rsq_f32_e32 v108, v108
	s_nop 0
	v_pk_mul_f32 v[100:101], v[100:101], v[108:109] op_sel_hi:[1,0]
	v_pk_mul_f32 v[102:103], v[102:103], v[108:109] op_sel_hi:[1,0]
	v_pk_mul_f32 v[110:111], v[98:99], v[108:109] op_sel_hi:[1,0]
	v_pk_mul_f32 v[104:105], v[104:105], v[108:109] op_sel_hi:[1,0]
	v_pk_mul_f32 v[100:101], v[8:9], v[100:101]
	v_pk_mul_f32 v[98:99], v[6:7], v[102:103]
	global_store_dwordx4 v[106:107], v[98:101], off sc1 nt
	s_nop 1
	v_pk_mul_f32 v[100:101], v[4:5], v[110:111]
	v_pk_mul_f32 v[98:99], v[2:3], v[104:105]
	global_store_dwordx4 v[106:107], v[98:101], off offset:512 sc1 nt
	s_nop 1
	v_or_b32_e32 v98, 32, v152
	v_ashrrev_i32_e32 v99, 31, v98
	v_mov_b32_e32 v100, 0
	v_mov_b32_e32 v101, 0
	s_nop 0
	s_waitcnt vmcnt(19)
	v_mov_b32_e32 v101, v198
	v_lshlrev_b64 v[98:99], 12, v[98:99]
	v_lshl_add_u64 v[98:99], s[48:49], 0, v[98:99]
	v_lshl_add_u64 v[98:99], v[150:151], 2, v[98:99]
	s_waitcnt lgkmcnt(0)
; __device__ __forceinline__ float rstd_of(float ss) { return __builtin_amdgcn_rsqf(ss * (1.0f / DM) + EPS); }
; __device__ __forceinline__ float atomic_read_f32(float* p) { return __hip_atomic_fetch_add(p, 0.0f, __ATOMIC_RELAXED, __HIP_MEMORY_SCOPE_AGENT); }
;     __device__ __forceinline__ void operator()(pg8::f32x4 (&acc)[2][2][4][2], const Unit& u, int wr, int wc, int fr, int fq) const {
;     ...
;         for (int ai = 0; ai < 2; ++ai)
; #pragma unroll
;             for (int m = 0; m < 4; ++m)
; #pragma unroll
;                 for (int p = 0; p < 2; ++p) { const int row = row0 + ai * HALF + m * 16 + 8 * p + rr; float s = 0.f; if (sl == 0) s = atomic_read_f32(SS2 + row); const float rs = rstd_of(__shfl(s, lane & ~7));
; #pragma unroll
;                     for (int bj = 0; bj < 2; ++bj) *(pg8::f32x4*)(YO + (size_t)row * DM + cbase + bj * HALF) = acc[ai][bj][m][p] * rs * gn[bj]; }
	v_fmamk_f32 v101, v101, 0x3a800000, v172
	v_rsq_f32_e32 v102, v101
	s_nop 0
	v_pk_mul_f32 v[90:91], v[90:91], v[102:103] op_sel_hi:[1,0]
	v_pk_mul_f32 v[104:105], v[92:93], v[102:103] op_sel_hi:[1,0]
	v_pk_mul_f32 v[94:95], v[94:95], v[102:103] op_sel_hi:[1,0]
	v_pk_mul_f32 v[96:97], v[96:97], v[102:103] op_sel_hi:[1,0]
	v_pk_mul_f32 v[92:93], v[8:9], v[90:91]
	v_pk_mul_f32 v[90:91], v[6:7], v[104:105]
	global_store_dwordx4 v[98:99], v[90:93], off sc1 nt
	s_nop 1
	v_pk_mul_f32 v[92:93], v[4:5], v[94:95]
	v_pk_mul_f32 v[90:91], v[2:3], v[96:97]
	global_store_dwordx4 v[98:99], v[90:93], off offset:512 sc1 nt
	s_nop 1
	v_or_b32_e32 v90, 40, v152
	v_ashrrev_i32_e32 v91, 31, v90
	s_nop 0
	s_waitcnt vmcnt(20)
	v_mov_b32_e32 v92, v199
	v_lshlrev_b64 v[90:91], 12, v[90:91]
	v_lshl_add_u64 v[90:91], s[48:49], 0, v[90:91]
	v_lshl_add_u64 v[90:91], v[150:151], 2, v[90:91]
	s_waitcnt lgkmcnt(0)
	v_fmamk_f32 v92, v92, 0x3a800000, v172
	v_rsq_f32_e32 v92, v92
	s_nop 0
	v_pk_mul_f32 v[84:85], v[84:85], v[92:93] op_sel_hi:[1,0]
	v_pk_mul_f32 v[86:87], v[86:87], v[92:93] op_sel_hi:[1,0]
	v_pk_mul_f32 v[94:95], v[82:83], v[92:93] op_sel_hi:[1,0]
	v_pk_mul_f32 v[88:89], v[88:89], v[92:93] op_sel_hi:[1,0]
	v_pk_mul_f32 v[84:85], v[8:9], v[84:85]
	v_pk_mul_f32 v[82:83], v[6:7], v[86:87]
	global_store_dwordx4 v[90:91], v[82:85], off sc1 nt
	s_nop 1
	v_pk_mul_f32 v[84:85], v[4:5], v[94:95]
	v_pk_mul_f32 v[82:83], v[2:3], v[88:89]
	global_store_dwordx4 v[90:91], v[82:85], off offset:512 sc1 nt
	s_nop 1
	v_or_b32_e32 v82, 48, v152
	v_ashrrev_i32_e32 v83, 31, v82
	v_mov_b32_e32 v84, 0
	v_mov_b32_e32 v85, 0
	s_nop 0
	s_waitcnt vmcnt(21)
	v_mov_b32_e32 v85, v200
	v_lshlrev_b64 v[82:83], 12, v[82:83]
	v_lshl_add_u64 v[82:83], s[48:49], 0, v[82:83]
	v_lshl_add_u64 v[82:83], v[150:151], 2, v[82:83]
	s_waitcnt lgkmcnt(0)
	v_fmamk_f32 v85, v85, 0x3a800000, v172
	v_rsq_f32_e32 v86, v85
	s_nop 0
	v_pk_mul_f32 v[74:75], v[74:75], v[86:87] op_sel_hi:[1,0]
	v_pk_mul_f32 v[88:89], v[76:77], v[86:87] op_sel_hi:[1,0]
	v_pk_mul_f32 v[78:79], v[78:79], v[86:87] op_sel_hi:[1,0]
	v_pk_mul_f32 v[80:81], v[80:81], v[86:87] op_sel_hi:[1,0]
	v_pk_mul_f32 v[76:77], v[8:9], v[74:75]
	v_pk_mul_f32 v[74:75], v[6:7], v[88:89]
	global_store_dwordx4 v[82:83], v[74:77], off sc1 nt
	s_nop 1
	v_pk_mul_f32 v[76:77], v[4:5], v[78:79]
	v_pk_mul_f32 v[74:75], v[2:3], v[80:81]
	global_store_dwordx4 v[82:83], v[74:77], off offset:512 sc1 nt
	s_nop 1
	v_or_b32_e32 v74, 56, v152
	v_ashrrev_i32_e32 v75, 31, v74
	s_nop 0
	s_waitcnt vmcnt(22)
	v_mov_b32_e32 v76, v201
	v_lshlrev_b64 v[74:75], 12, v[74:75]
	v_lshl_add_u64 v[74:75], s[48:49], 0, v[74:75]
	v_lshl_add_u64 v[74:75], v[150:151], 2, v[74:75]
	s_waitcnt lgkmcnt(0)
	v_fmamk_f32 v76, v76, 0x3a800000, v172
	v_rsq_f32_e32 v76, v76
	s_nop 0
	v_pk_mul_f32 v[68:69], v[68:69], v[76:77] op_sel_hi:[1,0]
	v_pk_mul_f32 v[70:71], v[70:71], v[76:77] op_sel_hi:[1,0]
	v_pk_mul_f32 v[78:79], v[66:67], v[76:77] op_sel_hi:[1,0]
	v_pk_mul_f32 v[72:73], v[72:73], v[76:77] op_sel_hi:[1,0]
	v_pk_mul_f32 v[68:69], v[8:9], v[68:69]
	v_pk_mul_f32 v[66:67], v[6:7], v[70:71]
	global_store_dwordx4 v[74:75], v[66:69], off sc1 nt
	s_nop 1
	v_pk_mul_f32 v[68:69], v[4:5], v[78:79]
	v_pk_mul_f32 v[66:67], v[2:3], v[72:73]
	global_store_dwordx4 v[74:75], v[66:69], off offset:512 sc1 nt
	s_nop 1
	v_add_u32_e32 v66, 0x80, v152
	v_ashrrev_i32_e32 v67, 31, v66
	v_mov_b32_e32 v68, 0
	v_mov_b32_e32 v69, 0
	s_nop 0
	s_waitcnt vmcnt(23)
	v_mov_b32_e32 v69, v202
	v_lshlrev_b64 v[66:67], 12, v[66:67]
	v_lshl_add_u64 v[66:67], s[48:49], 0, v[66:67]
	v_lshl_add_u64 v[66:67], v[150:151], 2, v[66:67]
	s_waitcnt lgkmcnt(0)
	v_fmamk_f32 v69, v69, 0x3a800000, v172
	v_rsq_f32_e32 v70, v69
	s_nop 0
	v_pk_mul_f32 v[58:59], v[58:59], v[70:71] op_sel_hi:[1,0]
	v_pk_mul_f32 v[72:73], v[60:61], v[70:71] op_sel_hi:[1,0]
	v_pk_mul_f32 v[62:63], v[62:63], v[70:71] op_sel_hi:[1,0]
	v_pk_mul_f32 v[64:65], v[64:65], v[70:71] op_sel_hi:[1,0]
	v_pk_mul_f32 v[60:61], v[8:9], v[58:59]
	v_pk_mul_f32 v[58:59], v[6:7], v[72:73]
	global_store_dwordx4 v[66:67], v[58:61], off sc1 nt
	s_nop 1
	v_pk_mul_f32 v[60:61], v[4:5], v[62:63]
	v_pk_mul_f32 v[58:59], v[2:3], v[64:65]
	global_store_dwordx4 v[66:67], v[58:61], off offset:512 sc1 nt
	s_nop 1
	v_add_u32_e32 v58, 0x88, v152
	v_ashrrev_i32_e32 v59, 31, v58
	s_nop 0
	s_waitcnt vmcnt(24)
	v_mov_b32_e32 v60, v203
	v_lshlrev_b64 v[58:59], 12, v[58:59]
	v_lshl_add_u64 v[58:59], s[48:49], 0, v[58:59]
	v_lshl_add_u64 v[58:59], v[150:151], 2, v[58:59]
	s_waitcnt lgkmcnt(0)
	v_fmamk_f32 v60, v60, 0x3a800000, v172
	v_rsq_f32_e32 v60, v60
	s_nop 0
	v_pk_mul_f32 v[52:53], v[52:53], v[60:61] op_sel_hi:[1,0]
	v_pk_mul_f32 v[54:55], v[54:55], v[60:61] op_sel_hi:[1,0]
	v_pk_mul_f32 v[62:63], v[50:51], v[60:61] op_sel_hi:[1,0]
	v_pk_mul_f32 v[56:57], v[56:57], v[60:61] op_sel_hi:[1,0]
	v_pk_mul_f32 v[52:53], v[8:9], v[52:53]
	v_pk_mul_f32 v[50:51], v[6:7], v[54:55]
	global_store_dwordx4 v[58:59], v[50:53], off sc1 nt
	s_nop 1
	v_pk_mul_f32 v[52:53], v[4:5], v[62:63]
	v_pk_mul_f32 v[50:51], v[2:3], v[56:57]
	global_store_dwordx4 v[58:59], v[50:53], off offset:512 sc1 nt
	s_nop 1
	v_add_u32_e32 v50, 0x90, v152
	v_ashrrev_i32_e32 v51, 31, v50
	v_mov_b32_e32 v52, 0
	v_mov_b32_e32 v53, 0
	s_nop 0
	s_waitcnt vmcnt(25)
; __device__ __forceinline__ float rstd_of(float ss) { return __builtin_amdgcn_rsqf(ss * (1.0f / DM) + EPS); }
; __device__ __forceinline__ float atomic_read_f32(float* p) { return __hip_atomic_fetch_add(p, 0.0f, __ATOMIC_RELAXED, __HIP_MEMORY_SCOPE_AGENT); }
;     __device__ __forceinline__ void operator()(pg8::f32x4 (&acc)[2][2][4][2], const Unit& u, int wr, int wc, int fr, int fq) const {
;     ...
;         for (int ai = 0; ai < 2; ++ai)
; #pragma unroll
;             for (int m = 0; m < 4; ++m)
; #pragma unroll
;                 for (int p = 0; p < 2; ++p) { const int row = row0 + ai * HALF + m * 16 + 8 * p + rr; float s = 0.f; if (sl == 0) s = atomic_read_f32(SS2 + row); const float rs = rstd_of(__shfl(s, lane & ~7));
; #pragma unroll
;                     for (int bj = 0; bj < 2; ++bj) *(pg8::f32x4*)(YO + (size_t)row * DM + cbase + bj * HALF) = acc[ai][bj][m][p] * rs * gn[bj]; }
	v_mov_b32_e32 v53, v204
	v_lshlrev_b64 v[50:51], 12, v[50:51]
	v_lshl_add_u64 v[50:51], s[48:49], 0, v[50:51]
	v_lshl_add_u64 v[50:51], v[150:151], 2, v[50:51]
	s_waitcnt lgkmcnt(0)
	v_fmamk_f32 v53, v53, 0x3a800000, v172
	v_rsq_f32_e32 v54, v53
	s_nop 0
	v_pk_mul_f32 v[42:43], v[42:43], v[54:55] op_sel_hi:[1,0]
	v_pk_mul_f32 v[56:57], v[44:45], v[54:55] op_sel_hi:[1,0]
	v_pk_mul_f32 v[46:47], v[46:47], v[54:55] op_sel_hi:[1,0]
	v_pk_mul_f32 v[48:49], v[48:49], v[54:55] op_sel_hi:[1,0]
	v_pk_mul_f32 v[44:45], v[8:9], v[42:43]
	v_pk_mul_f32 v[42:43], v[6:7], v[56:57]
	global_store_dwordx4 v[50:51], v[42:45], off sc1 nt
	s_nop 1
	v_pk_mul_f32 v[44:45], v[4:5], v[46:47]
	v_pk_mul_f32 v[42:43], v[2:3], v[48:49]
	global_store_dwordx4 v[50:51], v[42:45], off offset:512 sc1 nt
	s_nop 1
	v_add_u32_e32 v42, 0x98, v152
	v_ashrrev_i32_e32 v43, 31, v42
	s_nop 0
	s_waitcnt vmcnt(26)
	v_mov_b32_e32 v44, v205
	v_lshlrev_b64 v[42:43], 12, v[42:43]
	v_lshl_add_u64 v[42:43], s[48:49], 0, v[42:43]
	v_lshl_add_u64 v[42:43], v[150:151], 2, v[42:43]
	s_waitcnt lgkmcnt(0)
	v_fmamk_f32 v44, v44, 0x3a800000, v172
	v_rsq_f32_e32 v44, v44
	s_nop 0
	v_pk_mul_f32 v[36:37], v[36:37], v[44:45] op_sel_hi:[1,0]
	v_pk_mul_f32 v[38:39], v[38:39], v[44:45] op_sel_hi:[1,0]
	v_pk_mul_f32 v[46:47], v[34:35], v[44:45] op_sel_hi:[1,0]
	v_pk_mul_f32 v[40:41], v[40:41], v[44:45] op_sel_hi:[1,0]
	v_pk_mul_f32 v[36:37], v[8:9], v[36:37]
	v_pk_mul_f32 v[34:35], v[6:7], v[38:39]
	global_store_dwordx4 v[42:43], v[34:37], off sc1 nt
	s_nop 1
	v_pk_mul_f32 v[36:37], v[4:5], v[46:47]
	v_pk_mul_f32 v[34:35], v[2:3], v[40:41]
	global_store_dwordx4 v[42:43], v[34:37], off offset:512 sc1 nt
	s_nop 1
	v_add_u32_e32 v34, 0xa0, v152
	v_ashrrev_i32_e32 v35, 31, v34
	v_mov_b32_e32 v36, 0
	v_mov_b32_e32 v37, 0
	s_nop 0
	s_waitcnt vmcnt(27)
	v_mov_b32_e32 v37, v206
	v_lshlrev_b64 v[34:35], 12, v[34:35]
	v_lshl_add_u64 v[34:35], s[48:49], 0, v[34:35]
	v_lshl_add_u64 v[34:35], v[150:151], 2, v[34:35]
	s_waitcnt lgkmcnt(0)
	v_fmamk_f32 v37, v37, 0x3a800000, v172
	v_rsq_f32_e32 v38, v37
	s_nop 0
	v_pk_mul_f32 v[26:27], v[26:27], v[38:39] op_sel_hi:[1,0]
	v_pk_mul_f32 v[40:41], v[28:29], v[38:39] op_sel_hi:[1,0]
	v_pk_mul_f32 v[30:31], v[30:31], v[38:39] op_sel_hi:[1,0]
	v_pk_mul_f32 v[32:33], v[32:33], v[38:39] op_sel_hi:[1,0]
	v_pk_mul_f32 v[28:29], v[8:9], v[26:27]
	v_pk_mul_f32 v[26:27], v[6:7], v[40:41]
	global_store_dwordx4 v[34:35], v[26:29], off sc1 nt
	s_nop 1
	v_pk_mul_f32 v[28:29], v[4:5], v[30:31]
	v_pk_mul_f32 v[26:27], v[2:3], v[32:33]
	global_store_dwordx4 v[34:35], v[26:29], off offset:512 sc1 nt
	s_nop 1
	v_add_u32_e32 v26, 0xa8, v152
	v_ashrrev_i32_e32 v27, 31, v26
	s_nop 0
	s_waitcnt vmcnt(28)
	v_mov_b32_e32 v28, v207
	v_lshlrev_b64 v[26:27], 12, v[26:27]
	v_lshl_add_u64 v[26:27], s[48:49], 0, v[26:27]
	v_lshl_add_u64 v[26:27], v[150:151], 2, v[26:27]
	s_waitcnt lgkmcnt(0)
	v_fmamk_f32 v28, v28, 0x3a800000, v172
	v_rsq_f32_e32 v28, v28
	s_nop 0
	v_pk_mul_f32 v[20:21], v[20:21], v[28:29] op_sel_hi:[1,0]
	v_pk_mul_f32 v[22:23], v[22:23], v[28:29] op_sel_hi:[1,0]
	v_pk_mul_f32 v[30:31], v[18:19], v[28:29] op_sel_hi:[1,0]
	v_pk_mul_f32 v[24:25], v[24:25], v[28:29] op_sel_hi:[1,0]
	v_pk_mul_f32 v[20:21], v[8:9], v[20:21]
	v_pk_mul_f32 v[18:19], v[6:7], v[22:23]
	global_store_dwordx4 v[26:27], v[18:21], off sc1 nt
	s_nop 1
	v_pk_mul_f32 v[20:21], v[4:5], v[30:31]
	v_pk_mul_f32 v[18:19], v[2:3], v[24:25]
	global_store_dwordx4 v[26:27], v[18:21], off offset:512 sc1 nt
	s_nop 1
	v_add_u32_e32 v18, 0xb0, v152
	v_ashrrev_i32_e32 v19, 31, v18
	v_mov_b32_e32 v20, 0
	v_mov_b32_e32 v21, 0
	s_nop 0
	s_waitcnt vmcnt(29)
	v_mov_b32_e32 v21, v208
	v_lshlrev_b64 v[18:19], 12, v[18:19]
	v_lshl_add_u64 v[18:19], s[48:49], 0, v[18:19]
	v_lshl_add_u64 v[18:19], v[150:151], 2, v[18:19]
	s_waitcnt lgkmcnt(0)
	v_fmamk_f32 v21, v21, 0x3a800000, v172
	v_rsq_f32_e32 v22, v21
	s_nop 0
	v_pk_mul_f32 v[24:25], v[158:159], v[22:23] op_sel_hi:[1,0]
	v_pk_mul_f32 v[26:27], v[160:161], v[22:23] op_sel_hi:[1,0]
	v_pk_mul_f32 v[28:29], v[162:163], v[22:23] op_sel_hi:[1,0]
	v_pk_mul_f32 v[30:31], v[164:165], v[22:23] op_sel_hi:[1,0]
	v_pk_mul_f32 v[24:25], v[8:9], v[24:25]
	v_pk_mul_f32 v[22:23], v[6:7], v[26:27]
	global_store_dwordx4 v[18:19], v[22:25], off sc1 nt
	s_nop 1
	v_pk_mul_f32 v[24:25], v[4:5], v[28:29]
	v_pk_mul_f32 v[22:23], v[2:3], v[30:31]
	global_store_dwordx4 v[18:19], v[22:25], off offset:512 sc1 nt
	v_add_u32_e32 v18, 0xb8, v152
	v_ashrrev_i32_e32 v19, 31, v18
	s_nop 0
	s_waitcnt vmcnt(30)
	v_mov_b32_e32 v20, v209
	v_lshlrev_b64 v[18:19], 12, v[18:19]
	v_lshl_add_u64 v[18:19], s[48:49], 0, v[18:19]
	v_lshl_add_u64 v[18:19], v[150:151], 2, v[18:19]
	s_and_b64 vcc, exec, s[10:11]
	s_waitcnt lgkmcnt(0)
	v_fmamk_f32 v20, v20, 0x3a800000, v172
	v_rsq_f32_e32 v20, v20
	s_mov_b64 s[4:5], -1
	v_pk_mul_f32 v[12:13], v[12:13], v[20:21] op_sel_hi:[1,0]
	v_pk_mul_f32 v[14:15], v[14:15], v[20:21] op_sel_hi:[1,0]
	v_pk_mul_f32 v[10:11], v[10:11], v[20:21] op_sel_hi:[1,0]
	v_pk_mul_f32 v[16:17], v[16:17], v[20:21] op_sel_hi:[1,0]
	v_pk_mul_f32 v[8:9], v[8:9], v[12:13]
	v_pk_mul_f32 v[6:7], v[6:7], v[14:15]
	v_pk_mul_f32 v[4:5], v[4:5], v[10:11]
	v_pk_mul_f32 v[2:3], v[2:3], v[16:17]
	global_store_dwordx4 v[18:19], v[6:9], off sc1 nt
	global_store_dwordx4 v[18:19], v[2:5], off offset:512 sc1 nt
	s_cbranch_vccnz .LBB0_1056
	s_andn2_b64 vcc, exec, s[22:23]
	s_cbranch_vccnz .LBB0_1055
	s_barrier
	s_branch .LBB0_1055

; __device__ __forceinline__ float rstd_of(float ss) { return __builtin_amdgcn_rsqf(ss * (1.0f / DM) + EPS); }
; __device__ __forceinline__ float atomic_read_f32(float* p) { return __hip_atomic_fetch_add(p, 0.0f, __ATOMIC_RELAXED, __HIP_MEMORY_SCOPE_AGENT); }
; __device__ __forceinline__ void down_sample_tile(Frame& F, int tile, float* SS2, unsigned* cntb, float* YO) {
;     ...
;     float s = 0.f; if ((F.tid & 7) == 0) s = atomic_read_f32(SS2 + row);
;     const float rs = rstd_of(__shfl(s, F.lane & ~7));
;     *(f32x4v*)(YO + off) = (f32x4v){x0[0] * rs * ga[0], x0[1] * rs * ga[1], x0[2] * rs * ga[2], x0[3] * rs * ga[3]};
;     *(f32x4v*)(YO + off + 4) = (f32x4v){x1[0] * rs * gb[0], x1[1] * rs * gb[1], x1[2] * rs * gb[2], x1[3] * rs * gb[3]};
.LBB0_1140:
	s_or_b64 exec, exec, s[4:5]
	s_waitcnt vmcnt(0)
	ds_bpermute_b32 v20, v89, v22
	s_add_i32 s2, s52, s2
	v_lshl_add_u64 v[10:11], v[10:11], 2, s[48:49]
	s_cmpk_gt_i32 s2, 0xff
	s_waitcnt lgkmcnt(0)
	v_fmamk_f32 v20, v20, 0x3a800000, v93
	v_rsq_f32_e32 v20, v20
	s_nop 0
	v_pk_mul_f32 v[12:13], v[12:13], v[20:21] op_sel_hi:[1,0]
	v_pk_mul_f32 v[16:17], v[16:17], v[20:21] op_sel_hi:[1,0]
	v_pk_mul_f32 v[14:15], v[14:15], v[20:21] op_sel_hi:[1,0]
	v_pk_mul_f32 v[18:19], v[18:19], v[20:21] op_sel_hi:[1,0]
	v_pk_mul_f32 v[8:9], v[8:9], v[16:17]
	v_pk_mul_f32 v[6:7], v[6:7], v[12:13]
	v_pk_mul_f32 v[4:5], v[4:5], v[18:19]
	v_pk_mul_f32 v[2:3], v[2:3], v[14:15]
	global_store_dwordx4 v[10:11], v[6:9], off sc1 nt
	global_store_dwordx4 v[10:11], v[2:5], off offset:16 sc1 nt
	s_cbranch_scc1 .LBB0_1159

; __device__ __forceinline__ float rstd_of(float ss) { return __builtin_amdgcn_rsqf(ss * (1.0f / DM) + EPS); }
; __device__ __forceinline__ float atomic_read_f32(float* p) { return __hip_atomic_fetch_add(p, 0.0f, __ATOMIC_RELAXED, __HIP_MEMORY_SCOPE_AGENT); }
; __device__ __forceinline__ void down_sample_tile(Frame& F, int tile, float* SS2, unsigned* cntb, float* YO) {
;     ...
;     float s = 0.f; if ((F.tid & 7) == 0) s = atomic_read_f32(SS2 + row);
;     const float rs = rstd_of(__shfl(s, F.lane & ~7));
;     *(f32x4v*)(YO + off) = (f32x4v){x0[0] * rs * ga[0], x0[1] * rs * ga[1], x0[2] * rs * ga[2], x0[3] * rs * ga[3]};
;     *(f32x4v*)(YO + off + 4) = (f32x4v){x1[0] * rs * gb[0], x1[1] * rs * gb[1], x1[2] * rs * gb[2], x1[3] * rs * gb[3]};
.LBB0_1180:
	s_or_b64 exec, exec, s[2:3]
	v_and_or_b32 v0, v0, 56, v1
	v_lshlrev_b32_e32 v0, 2, v0
	s_waitcnt vmcnt(0)
	ds_bpermute_b32 v0, v0, v22
	v_mov_b32_e32 v1, 0x358637bd
	v_lshl_add_u64 v[10:11], v[10:11], 2, s[48:49]
	s_waitcnt lgkmcnt(0)
	v_fmac_f32_e32 v1, 0x3a800000, v0
	v_rsq_f32_e32 v0, v1
	s_nop 0
	v_pk_mul_f32 v[12:13], v[12:13], v[0:1] op_sel_hi:[1,0]
	v_pk_mul_f32 v[16:17], v[16:17], v[0:1] op_sel_hi:[1,0]
	v_pk_mul_f32 v[14:15], v[14:15], v[0:1] op_sel_hi:[1,0]
	v_pk_mul_f32 v[0:1], v[18:19], v[0:1] op_sel_hi:[1,0]
	v_pk_mul_f32 v[8:9], v[8:9], v[16:17]
	v_pk_mul_f32 v[6:7], v[6:7], v[12:13]
	v_pk_mul_f32 v[4:5], v[4:5], v[0:1]
	v_pk_mul_f32 v[2:3], v[2:3], v[14:15]
	global_store_dwordx4 v[10:11], v[6:9], off sc1 nt
	global_store_dwordx4 v[10:11], v[2:5], off offset:16 sc1 nt
